# cache_tail B-cache items: lane pairs exchange halves by DPP so the bf16 K/V image stores are 16 bytes per lane (8 dwordx4 instead of 16 dwordx2 per item)
# speedup vs baseline: 1.0192x; 1.0008x over previous
.LBB0_431:
	s_and_b64 vcc, exec, s[26:27]
	s_cbranch_vccz .LBB0_416
	s_load_dwordx4 s[28:31], s[20:21], 0x20
	v_and_b32_e32 v88, 1, v46
	v_cmp_ne_u32_e64 s[100:101], 0, v88
	s_lshl_b32 s26, s38, 10
	v_lshl_add_u32 v2, v46, 2, s26
	v_ashrrev_i32_e32 v3, 31, v2
	v_lshlrev_b64 v[2:3], 2, v[2:3]
	s_waitcnt lgkmcnt(0)
	v_lshl_add_u64 v[42:43], s[28:29], 0, v[2:3]
	v_lshl_add_u64 v[44:45], s[30:31], 0, v[2:3]
	global_load_dwordx4 v[26:29], v[42:43], off
	global_load_dwordx4 v[22:25], v[42:43], off offset:1024
	global_load_dwordx4 v[30:33], v[44:45], off
	global_load_dwordx4 v[18:21], v[44:45], off offset:1024
	global_load_dwordx4 v[10:13], v[42:43], off offset:2048
	global_load_dwordx4 v[6:9], v[42:43], off offset:3072
	global_load_dwordx4 v[14:17], v[44:45], off offset:2048
	global_load_dwordx4 v[2:5], v[44:45], off offset:3072
	v_lshl_add_u32 v44, s38, 8, v46
	v_mov_b32_e32 v39, v35
	v_mov_b32_e32 v41, v35
	v_lshl_add_u64 v[42:43], s[14:15], 0, v[38:39]
	v_lshl_add_u64 v[38:39], s[18:19], 0, v[40:41]
	v_lshlrev_b32_e32 v41, 2, v44
	v_ashrrev_i32_e32 v40, 16, v44
	v_lshrrev_b32_e32 v46, 7, v44
	v_bfe_u32 v50, v41, 6, 3
	v_bfe_u32 v51, v46, 5, 4
	v_lshl_or_b32 v50, v40, 3, v50
	v_mad_i32_i24 v50, v50, 17, v51
	v_ashrrev_i32_e32 v51, 31, v50
	v_bfe_u32 v48, v44, 7, 5
	v_lshlrev_b64 v[50:51], 12, v[50:51]
	v_mov_b32_e32 v47, v35
	v_mov_b32_e32 v49, v35
	v_lshlrev_b32_e32 v46, 4, v48
	v_lshlrev_b32_e32 v48, 6, v48
	v_lshl_add_u64 v[52:53], v[42:43], 0, v[50:51]
	v_lshl_add_u64 v[50:51], v[38:39], 0, v[50:51]
	v_lshl_add_u64 v[46:47], v[52:53], 0, v[46:47]
	v_lshl_add_u64 v[48:49], v[50:51], 0, v[48:49]
	v_bfe_u32 v45, v44, 7, 9
	v_mov_b32_e32 v37, v35
	v_lshl_add_u64 v[46:47], v[46:47], 0, v[34:35]
	v_cmp_lt_u32_e32 vcc, 31, v45
	v_lshl_add_u64 v[48:49], v[48:49], 0, v[36:37]
	s_waitcnt vmcnt(0)
	v_mov_b32_e32 v50, v26
	v_mov_b32_e32 v51, v22
	v_mov_b32_e32 v52, v30
	v_mov_b32_e32 v53, v18
	v_mov_b32_e32 v54, v10
	v_mov_b32_e32 v55, v6
	v_mov_b32_e32 v56, v14
	v_mov_b32_e32 v57, v2
	v_bfe_u32 v58, v26, 16, 1
	v_bfe_u32 v60, v28, 16, 1
	v_pk_add_f32 v[50:51], v[50:51], v[52:53]
	v_bfe_u32 v59, v27, 16, 1
	v_bfe_u32 v61, v29, 16, 1
	v_bfe_u32 v62, v30, 16, 1
	v_bfe_u32 v64, v32, 16, 1
	v_pk_add_f32 v[52:53], v[54:55], v[56:57]
	v_add3_u32 v54, v26, v58, s36
	v_add3_u32 v56, v28, v60, s36
	v_add_f32_e32 v50, 0, v50
	v_bfe_u32 v63, v31, 16, 1
	v_bfe_u32 v65, v33, 16, 1
	v_add3_u32 v55, v27, v59, s36
	v_add3_u32 v57, v29, v61, s36
	v_add3_u32 v58, v30, v62, s36
	v_add3_u32 v60, v32, v64, s36
	v_lshrrev_b32_e32 v54, 16, v54
	v_lshrrev_b32_e32 v56, 16, v56
	v_add_f32_e32 v62, v50, v51
	v_add3_u32 v59, v31, v63, s36
	v_add3_u32 v61, v33, v65, s36
	v_lshrrev_b32_e32 v58, 16, v58
	v_lshrrev_b32_e32 v60, 16, v60
	v_and_or_b32 v50, v55, s37, v54
	v_and_or_b32 v51, v57, s37, v56
	v_add_f32_e32 v52, v62, v52
	v_and_or_b32 v54, v59, s37, v58
	v_and_or_b32 v55, v61, s37, v60
	v_add_f32_e32 v52, v52, v53
	v_mov_b64_e32 v[70:71], v[50:51]
	v_mov_b64_e32 v[72:73], v[46:47]
	v_mov_b64_e32 v[74:75], v[54:55]
	v_mov_b64_e32 v[76:77], v[48:49]
	s_and_saveexec_b64 s[26:27], vcc
	s_cbranch_execz .LBB0_434
	v_lshl_or_b32 v40, v40, 9, v45
	v_subrev_u32_e32 v40, 32, v40
	v_and_b32_e32 v46, 0x1fc, v41
	v_ashrrev_i32_e32 v41, 31, v40
	v_lshlrev_b64 v[40:41], 11, v[40:41]
	v_lshl_or_b32 v40, v46, 2, v40
	v_lshl_add_u64 v[46:47], s[24:25], 0, v[40:41]
	global_store_dwordx4 v[46:47], v[26:29], off sc0 sc1
	s_nop 1
	v_lshl_add_u64 v[26:27], s[16:17], 0, v[40:41]
	global_store_dwordx4 v[26:27], v[30:33], off sc0 sc1
	s_nop 1
.LBB0_434:
	s_or_b64 exec, exec, s[26:27]
	v_add_u32_e32 v29, 64, v44
	v_lshlrev_b32_e32 v27, 2, v29
	v_ashrrev_i32_e32 v26, 16, v29
	v_lshrrev_b32_e32 v30, 7, v29
	v_bfe_u32 v31, v27, 6, 3
	v_lshl_or_b32 v31, v26, 3, v31
	v_bfe_u32 v30, v30, 5, 4
	v_mad_i32_i24 v30, v31, 17, v30
	v_ashrrev_i32_e32 v31, 31, v30
	v_bfe_u32 v28, v29, 7, 9
	v_lshlrev_b64 v[30:31], 12, v[30:31]
	v_bfe_u32 v29, v29, 7, 5
	v_lshl_add_u64 v[32:33], v[42:43], 0, v[30:31]
	v_lshlrev_b32_e32 v40, 4, v29
	v_mov_b32_e32 v41, v35
	v_lshl_add_u64 v[32:33], v[32:33], 0, v[40:41]
	v_bfe_u32 v40, v22, 16, 1
	v_add3_u32 v40, v22, v40, s36
	v_bfe_u32 v41, v23, 16, 1
	v_lshrrev_b32_e32 v40, 16, v40
	v_add3_u32 v41, v23, v41, s36
	v_and_or_b32 v40, v41, s37, v40
	v_bfe_u32 v41, v24, 16, 1
	v_add3_u32 v41, v24, v41, s36
	v_bfe_u32 v45, v25, 16, 1
	v_lshrrev_b32_e32 v41, 16, v41
	v_add3_u32 v45, v25, v45, s36
	v_lshl_add_u64 v[32:33], v[32:33], 0, v[34:35]
	v_and_or_b32 v41, v45, s37, v41
	v_cndmask_b32_e64 v78, v40, v70, s[100:101]
	v_cndmask_b32_e64 v79, v41, v71, s[100:101]
	v_subrev_u32_e32 v86, 8, v32
	s_nop 0
	v_mov_b32_dpp v80, v78 quad_perm:[1,0,3,2] row_mask:0xf bank_mask:0xf
	v_mov_b32_dpp v81, v79 quad_perm:[1,0,3,2] row_mask:0xf bank_mask:0xf
	v_cndmask_b32_e64 v86, v72, v86, s[100:101]
	v_cndmask_b32_e64 v87, v73, v33, s[100:101]
	v_cndmask_b32_e64 v82, v70, v80, s[100:101]
	v_cndmask_b32_e64 v83, v71, v81, s[100:101]
	v_cndmask_b32_e64 v84, v80, v40, s[100:101]
	v_cndmask_b32_e64 v85, v81, v41, s[100:101]
	global_store_dwordx4 v[86:87], v[82:85], off sc0 sc1
	s_nop 1
	v_lshl_add_u64 v[30:31], v[38:39], 0, v[30:31]
	v_lshlrev_b32_e32 v32, 6, v29
	v_mov_b32_e32 v33, v35
	v_bfe_u32 v29, v18, 16, 1
	v_lshl_add_u64 v[30:31], v[30:31], 0, v[32:33]
	v_add3_u32 v29, v18, v29, s36
	v_bfe_u32 v32, v19, 16, 1
	v_lshrrev_b32_e32 v29, 16, v29
	v_add3_u32 v32, v19, v32, s36
	v_and_or_b32 v32, v32, s37, v29
	v_bfe_u32 v29, v20, 16, 1
	v_add3_u32 v29, v20, v29, s36
	v_bfe_u32 v33, v21, 16, 1
	v_lshrrev_b32_e32 v29, 16, v29
	v_add3_u32 v33, v21, v33, s36
	v_lshl_add_u64 v[30:31], v[30:31], 0, v[36:37]
	v_and_or_b32 v33, v33, s37, v29
	v_cmp_lt_u32_e32 vcc, 31, v28
	v_cndmask_b32_e64 v78, v32, v74, s[100:101]
	v_cndmask_b32_e64 v79, v33, v75, s[100:101]
	v_subrev_u32_e32 v86, 8, v30
	s_nop 0
	v_mov_b32_dpp v80, v78 quad_perm:[1,0,3,2] row_mask:0xf bank_mask:0xf
	v_mov_b32_dpp v81, v79 quad_perm:[1,0,3,2] row_mask:0xf bank_mask:0xf
	v_cndmask_b32_e64 v86, v76, v86, s[100:101]
	v_cndmask_b32_e64 v87, v77, v31, s[100:101]
	v_cndmask_b32_e64 v82, v74, v80, s[100:101]
	v_cndmask_b32_e64 v83, v75, v81, s[100:101]
	v_cndmask_b32_e64 v84, v80, v32, s[100:101]
	v_cndmask_b32_e64 v85, v81, v33, s[100:101]
	global_store_dwordx4 v[86:87], v[82:85], off sc0 sc1
	s_nop 1
	s_and_saveexec_b64 s[26:27], vcc
	s_cbranch_execz .LBB0_436
	v_lshl_or_b32 v26, v26, 9, v28
	v_subrev_u32_e32 v26, 32, v26
	v_and_b32_e32 v29, 0x1fc, v27
	v_ashrrev_i32_e32 v27, 31, v26
	v_lshlrev_b64 v[26:27], 11, v[26:27]
	v_lshl_or_b32 v26, v29, 2, v26
	v_lshl_add_u64 v[28:29], s[24:25], 0, v[26:27]
	global_store_dwordx4 v[28:29], v[22:25], off sc0 sc1
	s_nop 1
	v_lshl_add_u64 v[22:23], s[16:17], 0, v[26:27]
	global_store_dwordx4 v[22:23], v[18:21], off sc0 sc1
	s_nop 1
.LBB0_436:
	s_or_b64 exec, exec, s[26:27]
	v_add_u32_e32 v21, 0x80, v44
	v_lshlrev_b32_e32 v19, 2, v21
	v_ashrrev_i32_e32 v18, 16, v21
	v_lshrrev_b32_e32 v22, 7, v21
	v_bfe_u32 v23, v19, 6, 3
	v_lshl_or_b32 v23, v18, 3, v23
	v_bfe_u32 v22, v22, 5, 4
	v_mad_i32_i24 v22, v23, 17, v22
	v_ashrrev_i32_e32 v23, 31, v22
	v_bfe_u32 v20, v21, 7, 9
	v_lshlrev_b64 v[22:23], 12, v[22:23]
	v_bfe_u32 v21, v21, 7, 5
	v_lshl_add_u64 v[24:25], v[42:43], 0, v[22:23]
	v_lshlrev_b32_e32 v26, 4, v21
	v_mov_b32_e32 v27, v35
	v_lshl_add_u64 v[24:25], v[24:25], 0, v[26:27]
	v_bfe_u32 v26, v10, 16, 1
	v_add3_u32 v26, v10, v26, s36
	v_bfe_u32 v27, v11, 16, 1
	v_lshrrev_b32_e32 v26, 16, v26
	v_add3_u32 v27, v11, v27, s36
	v_and_or_b32 v26, v27, s37, v26
	v_bfe_u32 v27, v12, 16, 1
	v_add3_u32 v27, v12, v27, s36
	v_bfe_u32 v28, v13, 16, 1
	v_lshrrev_b32_e32 v27, 16, v27
	v_add3_u32 v28, v13, v28, s36
	v_lshl_add_u64 v[24:25], v[24:25], 0, v[34:35]
	v_and_or_b32 v27, v28, s37, v27
	v_mov_b64_e32 v[70:71], v[26:27]
	v_mov_b64_e32 v[72:73], v[24:25]
	v_lshl_add_u64 v[22:23], v[38:39], 0, v[22:23]
	v_lshlrev_b32_e32 v24, 6, v21
	v_mov_b32_e32 v25, v35
	v_bfe_u32 v21, v14, 16, 1
	v_lshl_add_u64 v[22:23], v[22:23], 0, v[24:25]
	v_add3_u32 v21, v14, v21, s36
	v_bfe_u32 v24, v15, 16, 1
	v_lshrrev_b32_e32 v21, 16, v21
	v_add3_u32 v24, v15, v24, s36
	v_and_or_b32 v24, v24, s37, v21
	v_bfe_u32 v21, v16, 16, 1
	v_add3_u32 v21, v16, v21, s36
	v_bfe_u32 v25, v17, 16, 1
	v_lshrrev_b32_e32 v21, 16, v21
	v_add3_u32 v25, v17, v25, s36
	v_lshl_add_u64 v[22:23], v[22:23], 0, v[36:37]
	v_and_or_b32 v25, v25, s37, v21
	v_cmp_lt_u32_e32 vcc, 31, v20
	v_mov_b64_e32 v[74:75], v[24:25]
	v_mov_b64_e32 v[76:77], v[22:23]
	s_and_saveexec_b64 s[26:27], vcc
	s_cbranch_execz .LBB0_438
	v_lshl_or_b32 v18, v18, 9, v20
	v_subrev_u32_e32 v18, 32, v18
	v_and_b32_e32 v21, 0x1fc, v19
	v_ashrrev_i32_e32 v19, 31, v18
	v_lshlrev_b64 v[18:19], 11, v[18:19]
	v_lshl_or_b32 v18, v21, 2, v18
	v_lshl_add_u64 v[20:21], s[24:25], 0, v[18:19]
	global_store_dwordx4 v[20:21], v[10:13], off sc0 sc1
	s_nop 1
	v_lshl_add_u64 v[10:11], s[16:17], 0, v[18:19]
	global_store_dwordx4 v[10:11], v[14:17], off sc0 sc1
	s_nop 1
.LBB0_438:
	s_or_b64 exec, exec, s[26:27]
	v_add_u32_e32 v13, 0xc0, v44
	v_lshlrev_b32_e32 v11, 2, v13
	v_ashrrev_i32_e32 v10, 16, v13
	v_lshrrev_b32_e32 v14, 7, v13
	v_bfe_u32 v15, v11, 6, 3
	v_lshl_or_b32 v15, v10, 3, v15
	v_bfe_u32 v14, v14, 5, 4
	v_mad_i32_i24 v14, v15, 17, v14
	v_ashrrev_i32_e32 v15, 31, v14
	v_bfe_u32 v12, v13, 7, 9
	v_lshlrev_b64 v[14:15], 12, v[14:15]
	v_bfe_u32 v13, v13, 7, 5
	v_lshl_add_u64 v[16:17], v[42:43], 0, v[14:15]
	v_lshlrev_b32_e32 v18, 4, v13
	v_mov_b32_e32 v19, v35
	v_lshl_add_u64 v[16:17], v[16:17], 0, v[18:19]
	v_bfe_u32 v18, v6, 16, 1
	v_add3_u32 v18, v6, v18, s36
	v_bfe_u32 v19, v7, 16, 1
	v_lshrrev_b32_e32 v18, 16, v18
	v_add3_u32 v19, v7, v19, s36
	v_and_or_b32 v18, v19, s37, v18
	v_bfe_u32 v19, v8, 16, 1
	v_add3_u32 v19, v8, v19, s36
	v_bfe_u32 v20, v9, 16, 1
	v_lshrrev_b32_e32 v19, 16, v19
	v_add3_u32 v20, v9, v20, s36
	v_lshl_add_u64 v[16:17], v[16:17], 0, v[34:35]
	v_and_or_b32 v19, v20, s37, v19
	v_lshlrev_b32_e32 v34, 6, v13
	v_bfe_u32 v13, v2, 16, 1
	v_cndmask_b32_e64 v78, v18, v70, s[100:101]
	v_cndmask_b32_e64 v79, v19, v71, s[100:101]
	v_subrev_u32_e32 v86, 8, v16
	s_nop 0
	v_mov_b32_dpp v80, v78 quad_perm:[1,0,3,2] row_mask:0xf bank_mask:0xf
	v_mov_b32_dpp v81, v79 quad_perm:[1,0,3,2] row_mask:0xf bank_mask:0xf
	v_cndmask_b32_e64 v86, v72, v86, s[100:101]
	v_cndmask_b32_e64 v87, v73, v17, s[100:101]
	v_cndmask_b32_e64 v82, v70, v80, s[100:101]
	v_cndmask_b32_e64 v83, v71, v81, s[100:101]
	v_cndmask_b32_e64 v84, v80, v18, s[100:101]
	v_cndmask_b32_e64 v85, v81, v19, s[100:101]
	global_store_dwordx4 v[86:87], v[82:85], off sc0 sc1
	s_nop 1
	v_add3_u32 v13, v2, v13, s36
	v_bfe_u32 v16, v3, 16, 1
	v_lshrrev_b32_e32 v13, 16, v13
	v_add3_u32 v16, v3, v16, s36
	v_and_or_b32 v16, v16, s37, v13
	v_bfe_u32 v13, v4, 16, 1
	v_lshl_add_u64 v[14:15], v[38:39], 0, v[14:15]
	v_add3_u32 v13, v4, v13, s36
	v_bfe_u32 v17, v5, 16, 1
	v_lshl_add_u64 v[14:15], v[14:15], 0, v[34:35]
	v_lshrrev_b32_e32 v13, 16, v13
	v_add3_u32 v17, v5, v17, s36
	v_lshl_add_u64 v[14:15], v[14:15], 0, v[36:37]
	v_and_or_b32 v17, v17, s37, v13
	v_cmp_lt_u32_e32 vcc, 31, v12
	v_cndmask_b32_e64 v78, v16, v74, s[100:101]
	v_cndmask_b32_e64 v79, v17, v75, s[100:101]
	v_subrev_u32_e32 v86, 8, v14
	s_nop 0
	v_mov_b32_dpp v80, v78 quad_perm:[1,0,3,2] row_mask:0xf bank_mask:0xf
	v_mov_b32_dpp v81, v79 quad_perm:[1,0,3,2] row_mask:0xf bank_mask:0xf
	v_cndmask_b32_e64 v86, v76, v86, s[100:101]
	v_cndmask_b32_e64 v87, v77, v15, s[100:101]
	v_cndmask_b32_e64 v82, v74, v80, s[100:101]
	v_cndmask_b32_e64 v83, v75, v81, s[100:101]
	v_cndmask_b32_e64 v84, v80, v16, s[100:101]
	v_cndmask_b32_e64 v85, v81, v17, s[100:101]
	global_store_dwordx4 v[86:87], v[82:85], off sc0 sc1
	s_nop 1
	s_and_saveexec_b64 s[26:27], vcc
	s_cbranch_execz .LBB0_415
	v_lshl_or_b32 v10, v10, 9, v12
	v_subrev_u32_e32 v10, 32, v10
	v_and_b32_e32 v13, 0x1fc, v11
	v_ashrrev_i32_e32 v11, 31, v10
	v_lshlrev_b64 v[10:11], 11, v[10:11]
	v_lshl_or_b32 v10, v13, 2, v10
	v_lshl_add_u64 v[12:13], s[24:25], 0, v[10:11]
	global_store_dwordx4 v[12:13], v[6:9], off sc0 sc1
	s_nop 1
	v_lshl_add_u64 v[6:7], s[16:17], 0, v[10:11]
	global_store_dwordx4 v[6:7], v[2:5], off sc0 sc1
	s_nop 1
	s_branch .LBB0_415
